# MLA fast loop: row-sum adds of tile t as scalar v_add_f32 fillers behind QK MFMAs 2..12 of tile t+1 (exp results kept in spare VGPRs)
# baseline (speedup 1.0000x reference)
.LBB0_881:
	s_or_b64 exec, exec, s[42:43]
	v_pk_add_f32 v[48:49], v[48:49], v[54:55]
	v_pk_add_f32 v[64:65], v[128:129], v[64:65]
	v_pk_add_f32 v[48:49], v[58:59], v[48:49] op_sel_hi:[0,1]
	v_pk_add_f32 v[52:53], v[52:53], v[56:57]
	v_pk_add_f32 v[48:49], v[64:65], v[48:49]
	v_pk_add_f32 v[70:71], v[118:119], v[70:71]
	v_pk_add_f32 v[48:49], v[52:53], v[48:49]
	v_add_u32_e32 v54, v136, v135
	v_pk_add_f32 v[150:151], v[70:71], v[48:49]
	v_add_u32_e32 v48, 0x8c00, v166
	s_waitcnt vmcnt(0)
	ds_write2_b64 v48, v[74:75], v[76:77] offset1:2
	v_mul_lo_u32 v48, v54, 12
	v_sub_u32_e32 v52, v133, v48
	s_lshr_b32 s21, s61, 4
	v_lshlrev_b32_e32 v48, 3, v52
	v_lshlrev_b32_e32 v175, 4, v52
	v_mov_b64_e32 v[52:53], s[40:41]
	s_and_b32 s42, s21, 7
	v_mul_lo_u32 v174, v54, s56
	v_mad_i64_i32 v[54:55], s[40:41], v54, s51, v[52:53]
	v_pk_add_f32 v[50:51], v[50:51], v[62:63]
	v_ashrrev_i32_e32 v49, 31, v48
	v_mad_u64_u32 v[54:55], s[40:41], s42, v163, v[54:55]
	v_pk_add_f32 v[66:67], v[130:131], v[66:67]
	v_pk_add_f32 v[50:51], v[58:59], v[50:51] op_sel_hi:[0,1]
	v_lshl_add_u64 v[48:49], v[48:49], 1, v[54:55]
	v_pk_add_f32 v[56:57], v[116:117], v[68:69]
	v_pk_add_f32 v[50:51], v[66:67], v[50:51]
	v_mov_b32_e32 v154, v48
	v_mad_i64_i32 v[48:49], s[40:41], v59, s51, v[52:53]
	v_pk_add_f32 v[60:61], v[60:61], v[72:73]
	v_pk_add_f32 v[50:51], v[56:57], v[50:51]
	s_lshl_b32 s43, s42, 6
	v_mad_u64_u32 v[48:49], s[40:41], s42, v163, v[48:49]
	v_pk_add_f32 v[152:153], v[60:61], v[50:51]
	v_lshlrev_b32_e32 v50, 3, v112
	s_add_i32 s40, s47, s43
	v_ashrrev_i32_e32 v51, 31, v50
	s_ashr_i32 s41, s40, 31
	v_lshl_add_u64 v[48:49], v[50:51], 1, v[48:49]
	s_lshl_b64 s[40:41], s[40:41], 13
	v_and_b32_e32 v50, 7, v132
	v_mov_b32_e32 v156, v48
	v_lshl_add_u64 v[48:49], v[78:79], 0, s[40:41]
	v_lshlrev_b32_e32 v148, 4, v50
	v_lshl_add_u64 v[48:49], v[48:49], 0, v[148:149]
	v_mul_u32_u24_e32 v173, 0x90, v134
	s_mov_b32 s21, 1
	v_mov_b32_e32 v158, v48
	s_mov_b32 s42, 2
	s_mov_b32 s43, 1
	v_mov_b32_e32 v188, 0
	v_mov_b32_e32 v189, 0
	v_mov_b32_e32 v190, 0
	v_mov_b32_e32 v191, 0
	v_mov_b32_e32 v192, 0
	v_mov_b32_e32 v193, 0
	v_mov_b32_e32 v194, 0
	v_mov_b32_e32 v195, 0
	v_mov_b32_e32 v196, 0
	v_mov_b32_e32 v197, 0
	v_mov_b32_e32 v198, 0
	v_mov_b32_e32 v199, 0
	v_mov_b32_e32 v200, 0
	v_mov_b32_e32 v201, 0
	v_mov_b32_e32 v202, 0
	v_mov_b32_e32 v203, 0
	v_mov_b32_e32 v204, 0
	v_mov_b32_e32 v205, 0
	v_mov_b32_e32 v206, 0
	v_mov_b32_e32 v207, 0
	v_mov_b32_e32 v208, 0
	v_mov_b32_e32 v209, 0
	v_mov_b32_e32 v210, 0
	v_mov_b32_e32 v211, 0
	v_mov_b32_e32 v212, 0
	v_mov_b32_e32 v213, 0
	v_mov_b32_e32 v214, 0
	v_mov_b32_e32 v215, 0
	v_mov_b32_e32 v216, 0
	v_mov_b32_e32 v217, 0
	v_mov_b32_e32 v218, 0
	v_mov_b32_e32 v219, 0
	s_waitcnt lgkmcnt(0)
	s_barrier
	s_mov_b64 s[98:99], s[28:29]
	s_mov_b64 s[100:101], s[30:31]
	v_add_u32_e32 v244, v174, v175
	v_add_u32_e32 v245, v171, v172
	s_mov_b32 s71, 0x13b13b14
	s_mov_b32 s72, 0x15555556
	v_add_u32_e32 v148, s79, v184
	v_mul_hi_u32 v160, v148, s71
	v_mul_u32_u24_e32 v161, 13, v160
	v_sub_u32_e32 v161, v148, v161
	v_min_u32_e32 v161, 11, v161
	v_mul_u32_u24_e32 v160, 0x600, v160
	v_lshl_add_u32 v241, v161, 4, v160
	v_mul_hi_u32 v160, v148, s72
	v_mul_u32_u24_e32 v161, 12, v160
	v_sub_u32_e32 v161, v148, v161
	v_mul_u32_u24_e32 v160, 0x600, v160
	v_lshl_add_u32 v160, v161, 4, v160
	v_sub_u32_e32 v241, v241, v160
	v_add_u32_e32 v241, v241, v154
	v_add_u32_e32 v148, 0x200, v148
	v_mul_hi_u32 v160, v148, s71
	v_mul_u32_u24_e32 v161, 13, v160
	v_sub_u32_e32 v161, v148, v161
	v_min_u32_e32 v161, 11, v161
	v_mul_u32_u24_e32 v160, 0x600, v160
	v_lshl_add_u32 v242, v161, 4, v160
	v_mul_hi_u32 v160, v148, s72
	v_mul_u32_u24_e32 v161, 12, v160
	v_sub_u32_e32 v161, v148, v161
	v_mul_u32_u24_e32 v160, 0x600, v160
	v_lshl_add_u32 v160, v161, 4, v160
	v_sub_u32_e32 v242, v242, v160
	v_add_u32_e32 v242, v242, v156
	s_lshl_b32 s70, s79, 4
	s_add_i32 s73, s70, 0x2000
	s_cmpk_lt_u32 s79, 0x140
	s_cselect_b32 s73, s73, 0x12000
	s_cselect_b32 s74, 0x3400, 0
	s_cmp_eq_u32 s65, 0
	s_cbranch_scc0 .Lmlac_loop
.Lmla_loop:
	ds_read_b128 v[48:51], v169 offset:13312
	ds_read_b128 v[52:55], v169 offset:13344
	ds_read_b128 v[116:119], v169 offset:19968
	ds_read_b128 v[120:123], v169 offset:20000
	s_mov_b32 m0, s70
	s_nop 0
	global_load_lds_dwordx4 v241, s[98:99]
	s_mov_b32 m0, s73
	global_load_dwordx4 v[112:115], v158, s[100:101]
	global_load_lds_dwordx4 v242, s[98:99]
	s_add_u32 s98, s98, 0x18000
	s_addc_u32 s99, s99, 0
	s_waitcnt lgkmcnt(3)
	v_mfma_f32_32x32x16_bf16 v[64:79], v[48:51], v[100:103], v[32:47]
	ds_read_b128 v[124:127], v169 offset:13376
	ds_read_b128 v[128:131], v169 offset:13408
	ds_read_b128 v[132:135], v169 offset:20032
	ds_read_b128 v[136:139], v169 offset:20064
	s_waitcnt lgkmcnt(4)
	v_mfma_f32_32x32x16_bf16 v[64:79], v[52:55], v[96:99], v[64:79]
	v_add_f32_e32 v220, v190, v206
	v_add_f32_e32 v221, v191, v207
	v_add_f32_e32 v222, v188, v202
	v_mfma_f32_32x32x16_bf16 v[48:63], v[116:119], v[100:103], v[32:47]
	v_add_f32_e32 v223, v189, v203
	v_add_f32_e32 v220, v152, v220
	v_add_f32_e32 v221, v153, v221
	v_mfma_f32_32x32x16_bf16 v[48:63], v[120:123], v[96:99], v[48:63]
	v_add_f32_e32 v224, v192, v208
	v_add_f32_e32 v225, v193, v209
	v_add_f32_e32 v222, v150, v222
	s_waitcnt lgkmcnt(1)
	v_mfma_f32_32x32x16_bf16 v[64:79], v[124:127], v[92:95], v[64:79]
	v_add_f32_e32 v223, v151, v223
	v_add_f32_e32 v226, v194, v210
	v_add_f32_e32 v227, v195, v211
	v_mfma_f32_32x32x16_bf16 v[48:63], v[132:135], v[92:95], v[48:63]
	v_add_f32_e32 v220, v224, v220
	v_add_f32_e32 v221, v225, v221
	v_add_f32_e32 v224, v196, v212
	v_mfma_f32_32x32x16_bf16 v[64:79], v[128:131], v[88:91], v[64:79]
	v_add_f32_e32 v225, v197, v213
	v_add_f32_e32 v226, v226, v222
	v_add_f32_e32 v227, v227, v223
	ds_read_b128 v[116:119], v169 offset:13440
	ds_read_b128 v[120:123], v169 offset:13472
	ds_read_b128 v[128:131], v169 offset:20096
	ds_read_b128 v[176:179], v169 offset:20128
	s_waitcnt lgkmcnt(3)
	v_mfma_f32_32x32x16_bf16 v[48:63], v[136:139], v[88:91], v[48:63]
	v_add_f32_e32 v222, v218, v204
	v_add_f32_e32 v223, v219, v205
	v_add_f32_e32 v220, v224, v220
	v_mfma_f32_32x32x16_bf16 v[64:79], v[116:119], v[84:87], v[64:79]
	v_add_f32_e32 v221, v225, v221
	v_add_f32_e32 v224, v198, v214
	v_add_f32_e32 v225, v199, v215
	ds_read_b128 v[136:139], v170 offset:35840
	ds_read_b128 v[124:127], v170 offset:35872
	s_waitcnt lgkmcnt(3)
	v_mfma_f32_32x32x16_bf16 v[48:63], v[128:131], v[84:87], v[48:63]
	v_add_f32_e32 v226, v222, v226
	v_add_f32_e32 v227, v223, v227
	v_add_f32_e32 v228, v200, v216
	v_mfma_f32_32x32x16_bf16 v[64:79], v[120:123], v[80:83], v[64:79]
	v_add_f32_e32 v229, v201, v217
	v_add_f32_e32 v152, v224, v220
	v_add_f32_e32 v153, v225, v221
	ds_read_b128 v[132:135], v170 offset:35904
	ds_read_b128 v[120:123], v170 offset:35936
	ds_read_b128 v[144:147], v170 offset:40448
	ds_read_b128 v[140:143], v170 offset:40480
	ds_read_b128 v[128:131], v170 offset:40512
	ds_read_b128 v[116:119], v170 offset:40544
	s_waitcnt lgkmcnt(8)
	v_mfma_f32_32x32x16_bf16 v[48:63], v[176:179], v[80:83], v[48:63]
	v_add_f32_e32 v150, v228, v226
	v_add_f32_e32 v151, v229, v227
	s_add_i32 s43, s43, 1
	s_nop 3
	v_exp_f32_e32 v188, v64
	v_exp_f32_e32 v189, v65
	v_exp_f32_e32 v190, v66
	v_exp_f32_e32 v191, v67
	v_exp_f32_e32 v194, v68
	v_exp_f32_e32 v195, v69
	v_exp_f32_e32 v192, v70
	v_exp_f32_e32 v193, v71
	v_cvt_pk_bf16_f32 v176, v188, v189
	v_cvt_pk_bf16_f32 v177, v190, v191
	v_cvt_pk_bf16_f32 v178, v194, v195
	v_cvt_pk_bf16_f32 v179, v192, v193
	v_exp_f32_e32 v196, v74
	v_exp_f32_e32 v197, v75
	s_waitcnt lgkmcnt(0)
	v_mfma_f32_32x32x16_bf16 v[16:31], v[136:139], v[176:179], v[16:31]
	v_exp_f32_e32 v218, v72
	v_exp_f32_e32 v219, v73
	v_exp_f32_e32 v200, v76
	v_exp_f32_e32 v201, v77
	v_exp_f32_e32 v198, v78
	v_exp_f32_e32 v199, v79
	v_exp_f32_e32 v202, v48
	v_mfma_f32_32x32x16_bf16 v[0:15], v[144:147], v[176:179], v[0:15]
	v_cvt_pk_bf16_f32 v144, v218, v219
	v_cvt_pk_bf16_f32 v145, v196, v197
	v_cvt_pk_bf16_f32 v146, v200, v201
	v_cvt_pk_bf16_f32 v147, v198, v199
	v_exp_f32_e32 v203, v49
	v_exp_f32_e32 v206, v50
	v_exp_f32_e32 v207, v51
	v_mfma_f32_32x32x16_bf16 v[16:31], v[124:127], v[144:147], v[16:31]
	v_exp_f32_e32 v210, v52
	v_exp_f32_e32 v211, v53
	v_exp_f32_e32 v208, v54
	v_exp_f32_e32 v209, v55
	v_cvt_pk_bf16_f32 v124, v202, v203
	v_cvt_pk_bf16_f32 v125, v206, v207
	v_cvt_pk_bf16_f32 v126, v210, v211
	v_mfma_f32_32x32x16_bf16 v[0:15], v[140:143], v[144:147], v[0:15]
	v_cvt_pk_bf16_f32 v127, v208, v209
	v_exp_f32_e32 v204, v56
	v_exp_f32_e32 v205, v57
	v_exp_f32_e32 v212, v58
	v_exp_f32_e32 v213, v59
	v_exp_f32_e32 v216, v60
	v_exp_f32_e32 v217, v61
	v_mfma_f32_32x32x16_bf16 v[16:31], v[132:135], v[124:127], v[16:31]
	v_exp_f32_e32 v214, v62
	v_exp_f32_e32 v215, v63
	v_cvt_pk_bf16_f32 v60, v204, v205
	v_cvt_pk_bf16_f32 v61, v212, v213
	v_cvt_pk_bf16_f32 v62, v216, v217
	v_cvt_pk_bf16_f32 v63, v214, v215
	v_mfma_f32_32x32x16_bf16 v[0:15], v[128:131], v[124:127], v[0:15]
	v_mfma_f32_32x32x16_bf16 v[16:31], v[120:123], v[60:63], v[16:31]
	v_mfma_f32_32x32x16_bf16 v[0:15], v[116:119], v[60:63], v[0:15]
	s_waitcnt vmcnt(0)
	ds_write2_b64 v247, v[112:113], v[114:115] offset1:2
	s_waitcnt lgkmcnt(0)
	s_barrier
	ds_read_b128 v[48:51], v169
	ds_read_b128 v[52:55], v169 offset:32
	ds_read_b128 v[116:119], v169 offset:6656
	ds_read_b128 v[120:123], v169 offset:6688
	s_add_i32 m0, s70, 13312
	s_nop 0
	global_load_lds_dwordx4 v241, s[98:99]
	s_add_i32 m0, s73, s74
	global_load_dwordx4 v[112:115], v158, s[100:101] offset:128
	global_load_lds_dwordx4 v242, s[98:99]
	s_add_u32 s98, s98, 0x18000
	s_addc_u32 s99, s99, 0
	s_waitcnt lgkmcnt(3)
	v_mfma_f32_32x32x16_bf16 v[64:79], v[48:51], v[100:103], v[32:47]
	ds_read_b128 v[124:127], v169 offset:64
	ds_read_b128 v[128:131], v169 offset:96
	ds_read_b128 v[132:135], v169 offset:6720
	ds_read_b128 v[136:139], v169 offset:6752
	s_waitcnt lgkmcnt(4)
	v_mfma_f32_32x32x16_bf16 v[64:79], v[52:55], v[96:99], v[64:79]
	v_add_f32_e32 v220, v190, v206
	v_add_f32_e32 v221, v191, v207
	v_add_f32_e32 v222, v188, v202
	v_mfma_f32_32x32x16_bf16 v[48:63], v[116:119], v[100:103], v[32:47]
	v_add_f32_e32 v223, v189, v203
	v_add_f32_e32 v220, v152, v220
	v_add_f32_e32 v221, v153, v221
	v_mfma_f32_32x32x16_bf16 v[48:63], v[120:123], v[96:99], v[48:63]
	v_add_f32_e32 v224, v192, v208
	v_add_f32_e32 v225, v193, v209
	v_add_f32_e32 v222, v150, v222
	s_waitcnt lgkmcnt(1)
	v_mfma_f32_32x32x16_bf16 v[64:79], v[124:127], v[92:95], v[64:79]
	v_add_f32_e32 v223, v151, v223
	v_add_f32_e32 v226, v194, v210
	v_add_f32_e32 v227, v195, v211
	v_mfma_f32_32x32x16_bf16 v[48:63], v[132:135], v[92:95], v[48:63]
	v_add_f32_e32 v220, v224, v220
	v_add_f32_e32 v221, v225, v221
	v_add_f32_e32 v224, v196, v212
	v_mfma_f32_32x32x16_bf16 v[64:79], v[128:131], v[88:91], v[64:79]
	v_add_f32_e32 v225, v197, v213
	v_add_f32_e32 v226, v226, v222
	v_add_f32_e32 v227, v227, v223
	ds_read_b128 v[116:119], v169 offset:128
	ds_read_b128 v[120:123], v169 offset:160
	ds_read_b128 v[128:131], v169 offset:6784
	ds_read_b128 v[176:179], v169 offset:6816
	s_waitcnt lgkmcnt(3)
	v_mfma_f32_32x32x16_bf16 v[48:63], v[136:139], v[88:91], v[48:63]
	v_add_f32_e32 v222, v218, v204
	v_add_f32_e32 v223, v219, v205
	v_add_f32_e32 v220, v224, v220
	v_mfma_f32_32x32x16_bf16 v[64:79], v[116:119], v[84:87], v[64:79]
	v_add_f32_e32 v221, v225, v221
	v_add_f32_e32 v224, v198, v214
	v_add_f32_e32 v225, v199, v215
	ds_read_b128 v[136:139], v170 offset:45056
	ds_read_b128 v[124:127], v170 offset:45088
	s_waitcnt lgkmcnt(3)
; #define AT_QK_LD0(kb_) do { if constexpr (NEGM) { const LAS unsigned char* kbp_ = Kl + (kb_) * KBUF + r32 * KROWB + hi * 16; AT_KLD2(0); __builtin_amdgcn_sched_barrier(0); } } while (0)
; template <int DQK, int DV, int RH, bool NEGM> ...
;     ...
;         for (int t = 0; t < NT; ++t) {
;             const int kb = t & 1;
;             if (t + 1 < NT) AT_GLOAD(t + 1);
;             f32x16 p[RH][2];
;             AT_QK_LD0(kb); AT_QK(kb); AT_VLOAD(vs_cur); AT_SOFTMAX(); AT_PV(vs_cur);
;             if (t + 1 < NT) AT_LSTORE(kb ^ 1, vs_next);
;             __syncthreads();
;             vs_prev = vs_cur; vs_cur = vs_next; vs_next = (vs_next == 2) ? 0 : vs_next + 1;
	v_mfma_f32_32x32x16_bf16 v[48:63], v[128:131], v[84:87], v[48:63]
	v_add_f32_e32 v226, v222, v226
	v_add_f32_e32 v227, v223, v227
	v_add_f32_e32 v228, v200, v216
	v_mfma_f32_32x32x16_bf16 v[64:79], v[120:123], v[80:83], v[64:79]
	v_add_f32_e32 v229, v201, v217
	v_add_f32_e32 v152, v224, v220
	v_add_f32_e32 v153, v225, v221
	ds_read_b128 v[132:135], v170 offset:45120
	ds_read_b128 v[120:123], v170 offset:45152
	ds_read_b128 v[144:147], v170 offset:49664
	ds_read_b128 v[140:143], v170 offset:49696
	ds_read_b128 v[128:131], v170 offset:49728
	ds_read_b128 v[116:119], v170 offset:49760
	s_waitcnt lgkmcnt(8)
	v_mfma_f32_32x32x16_bf16 v[48:63], v[176:179], v[80:83], v[48:63]
	v_add_f32_e32 v150, v228, v226
	v_add_f32_e32 v151, v229, v227
	s_add_i32 s43, s43, 1
	s_nop 3
	v_exp_f32_e32 v188, v64
	v_exp_f32_e32 v189, v65
	v_exp_f32_e32 v190, v66
	v_exp_f32_e32 v191, v67
	v_exp_f32_e32 v194, v68
	v_exp_f32_e32 v195, v69
	v_exp_f32_e32 v192, v70
	v_exp_f32_e32 v193, v71
	v_cvt_pk_bf16_f32 v176, v188, v189
	v_cvt_pk_bf16_f32 v177, v190, v191
	v_cvt_pk_bf16_f32 v178, v194, v195
	v_cvt_pk_bf16_f32 v179, v192, v193
	v_exp_f32_e32 v196, v74
	v_exp_f32_e32 v197, v75
	s_waitcnt lgkmcnt(0)
	v_mfma_f32_32x32x16_bf16 v[16:31], v[136:139], v[176:179], v[16:31]
	v_exp_f32_e32 v218, v72
	v_exp_f32_e32 v219, v73
	v_exp_f32_e32 v200, v76
	v_exp_f32_e32 v201, v77
	v_exp_f32_e32 v198, v78
	v_exp_f32_e32 v199, v79
	v_exp_f32_e32 v202, v48
	v_mfma_f32_32x32x16_bf16 v[0:15], v[144:147], v[176:179], v[0:15]
	v_cvt_pk_bf16_f32 v144, v218, v219
	v_cvt_pk_bf16_f32 v145, v196, v197
	v_cvt_pk_bf16_f32 v146, v200, v201
	v_cvt_pk_bf16_f32 v147, v198, v199
	v_exp_f32_e32 v203, v49
	v_exp_f32_e32 v206, v50
	v_exp_f32_e32 v207, v51
	v_mfma_f32_32x32x16_bf16 v[16:31], v[124:127], v[144:147], v[16:31]
	v_exp_f32_e32 v210, v52
	v_exp_f32_e32 v211, v53
	v_exp_f32_e32 v208, v54
	v_exp_f32_e32 v209, v55
	v_cvt_pk_bf16_f32 v124, v202, v203
	v_cvt_pk_bf16_f32 v125, v206, v207
	v_cvt_pk_bf16_f32 v126, v210, v211
	v_mfma_f32_32x32x16_bf16 v[0:15], v[140:143], v[144:147], v[0:15]
	v_cvt_pk_bf16_f32 v127, v208, v209
	v_exp_f32_e32 v204, v56
	v_exp_f32_e32 v205, v57
	v_exp_f32_e32 v212, v58
	v_exp_f32_e32 v213, v59
	v_exp_f32_e32 v216, v60
	v_exp_f32_e32 v217, v61
	v_mfma_f32_32x32x16_bf16 v[16:31], v[132:135], v[124:127], v[16:31]
	v_exp_f32_e32 v214, v62
	v_exp_f32_e32 v215, v63
	v_cvt_pk_bf16_f32 v60, v204, v205
	v_cvt_pk_bf16_f32 v61, v212, v213
	v_cvt_pk_bf16_f32 v62, v216, v217
	v_cvt_pk_bf16_f32 v63, v214, v215
	v_mfma_f32_32x32x16_bf16 v[0:15], v[128:131], v[124:127], v[0:15]
	v_mfma_f32_32x32x16_bf16 v[16:31], v[120:123], v[60:63], v[16:31]
	v_mfma_f32_32x32x16_bf16 v[0:15], v[116:119], v[60:63], v[0:15]
	s_waitcnt vmcnt(0)
	ds_write2_b64 v243, v[112:113], v[114:115] offset1:2
	s_cmp_lg_u32 s43, 63
	s_waitcnt lgkmcnt(0)
	s_barrier
	s_cbranch_scc0 .Lmla_exit
	ds_read_b128 v[48:51], v169 offset:13312
	ds_read_b128 v[52:55], v169 offset:13344
	ds_read_b128 v[116:119], v169 offset:19968
	ds_read_b128 v[120:123], v169 offset:20000
	s_mov_b32 m0, s70
	s_nop 0
	global_load_lds_dwordx4 v241, s[98:99]
	s_mov_b32 m0, s73
	global_load_dwordx4 v[112:115], v158, s[100:101] offset:256
	global_load_lds_dwordx4 v242, s[98:99]
	s_add_u32 s98, s98, 0x18000
	s_addc_u32 s99, s99, 0
	s_waitcnt lgkmcnt(3)
	v_mfma_f32_32x32x16_bf16 v[64:79], v[48:51], v[100:103], v[32:47]
	ds_read_b128 v[124:127], v169 offset:13376
	ds_read_b128 v[128:131], v169 offset:13408
	ds_read_b128 v[132:135], v169 offset:20032
	ds_read_b128 v[136:139], v169 offset:20064
	s_waitcnt lgkmcnt(4)
	v_mfma_f32_32x32x16_bf16 v[64:79], v[52:55], v[96:99], v[64:79]
	v_add_f32_e32 v220, v190, v206
	v_add_f32_e32 v221, v191, v207
	v_add_f32_e32 v222, v188, v202
	v_mfma_f32_32x32x16_bf16 v[48:63], v[116:119], v[100:103], v[32:47]
	v_add_f32_e32 v223, v189, v203
	v_add_f32_e32 v220, v152, v220
	v_add_f32_e32 v221, v153, v221
	v_mfma_f32_32x32x16_bf16 v[48:63], v[120:123], v[96:99], v[48:63]
	v_add_f32_e32 v224, v192, v208
	v_add_f32_e32 v225, v193, v209
	v_add_f32_e32 v222, v150, v222
	s_waitcnt lgkmcnt(1)
	v_mfma_f32_32x32x16_bf16 v[64:79], v[124:127], v[92:95], v[64:79]
	v_add_f32_e32 v223, v151, v223
	v_add_f32_e32 v226, v194, v210
	v_add_f32_e32 v227, v195, v211
	v_mfma_f32_32x32x16_bf16 v[48:63], v[132:135], v[92:95], v[48:63]
	v_add_f32_e32 v220, v224, v220
	v_add_f32_e32 v221, v225, v221
	v_add_f32_e32 v224, v196, v212
	v_mfma_f32_32x32x16_bf16 v[64:79], v[128:131], v[88:91], v[64:79]
	v_add_f32_e32 v225, v197, v213
	v_add_f32_e32 v226, v226, v222
	v_add_f32_e32 v227, v227, v223
	ds_read_b128 v[116:119], v169 offset:13440
	ds_read_b128 v[120:123], v169 offset:13472
	ds_read_b128 v[128:131], v169 offset:20096
	ds_read_b128 v[176:179], v169 offset:20128
	s_waitcnt lgkmcnt(3)
	v_mfma_f32_32x32x16_bf16 v[48:63], v[136:139], v[88:91], v[48:63]
	v_add_f32_e32 v222, v218, v204
	v_add_f32_e32 v223, v219, v205
	v_add_f32_e32 v220, v224, v220
	v_mfma_f32_32x32x16_bf16 v[64:79], v[116:119], v[84:87], v[64:79]
	v_add_f32_e32 v221, v225, v221
	v_add_f32_e32 v224, v198, v214
	v_add_f32_e32 v225, v199, v215
	ds_read_b128 v[136:139], v170 offset:26624
	ds_read_b128 v[124:127], v170 offset:26656
	s_waitcnt lgkmcnt(3)
	v_mfma_f32_32x32x16_bf16 v[48:63], v[128:131], v[84:87], v[48:63]
	v_add_f32_e32 v226, v222, v226
	v_add_f32_e32 v227, v223, v227
	v_add_f32_e32 v228, v200, v216
	v_mfma_f32_32x32x16_bf16 v[64:79], v[120:123], v[80:83], v[64:79]
	v_add_f32_e32 v229, v201, v217
	v_add_f32_e32 v152, v224, v220
	v_add_f32_e32 v153, v225, v221
	ds_read_b128 v[132:135], v170 offset:26688
	ds_read_b128 v[120:123], v170 offset:26720
	ds_read_b128 v[144:147], v170 offset:31232
	ds_read_b128 v[140:143], v170 offset:31264
	ds_read_b128 v[128:131], v170 offset:31296
	ds_read_b128 v[116:119], v170 offset:31328
	s_waitcnt lgkmcnt(8)
; #define AT_QK_LD0(kb_) do { if constexpr (NEGM) { const LAS unsigned char* kbp_ = Kl + (kb_) * KBUF + r32 * KROWB + hi * 16; AT_KLD2(0); __builtin_amdgcn_sched_barrier(0); } } while (0)
; template <int DQK, int DV, int RH, bool NEGM> ...
;     ...
;         for (int t = 0; t < NT; ++t) {
;             const int kb = t & 1;
;             if (t + 1 < NT) AT_GLOAD(t + 1);
;             f32x16 p[RH][2];
;             AT_QK_LD0(kb); AT_QK(kb); AT_VLOAD(vs_cur); AT_SOFTMAX(); AT_PV(vs_cur);
;             if (t + 1 < NT) AT_LSTORE(kb ^ 1, vs_next);
;             __syncthreads();
;             vs_prev = vs_cur; vs_cur = vs_next; vs_next = (vs_next == 2) ? 0 : vs_next + 1;
	v_mfma_f32_32x32x16_bf16 v[48:63], v[176:179], v[80:83], v[48:63]
	v_add_f32_e32 v150, v228, v226
	v_add_f32_e32 v151, v229, v227
	s_add_i32 s43, s43, 1
	s_nop 3
	v_exp_f32_e32 v188, v64
	v_exp_f32_e32 v189, v65
	v_exp_f32_e32 v190, v66
	v_exp_f32_e32 v191, v67
	v_exp_f32_e32 v194, v68
	v_exp_f32_e32 v195, v69
	v_exp_f32_e32 v192, v70
	v_exp_f32_e32 v193, v71
	v_cvt_pk_bf16_f32 v176, v188, v189
	v_cvt_pk_bf16_f32 v177, v190, v191
	v_cvt_pk_bf16_f32 v178, v194, v195
	v_cvt_pk_bf16_f32 v179, v192, v193
	v_exp_f32_e32 v196, v74
	v_exp_f32_e32 v197, v75
	s_waitcnt lgkmcnt(0)
	v_mfma_f32_32x32x16_bf16 v[16:31], v[136:139], v[176:179], v[16:31]
	v_exp_f32_e32 v218, v72
	v_exp_f32_e32 v219, v73
	v_exp_f32_e32 v200, v76
	v_exp_f32_e32 v201, v77
	v_exp_f32_e32 v198, v78
	v_exp_f32_e32 v199, v79
	v_exp_f32_e32 v202, v48
	v_mfma_f32_32x32x16_bf16 v[0:15], v[144:147], v[176:179], v[0:15]
	v_cvt_pk_bf16_f32 v144, v218, v219
	v_cvt_pk_bf16_f32 v145, v196, v197
	v_cvt_pk_bf16_f32 v146, v200, v201
	v_cvt_pk_bf16_f32 v147, v198, v199
	v_exp_f32_e32 v203, v49
	v_exp_f32_e32 v206, v50
	v_exp_f32_e32 v207, v51
	v_mfma_f32_32x32x16_bf16 v[16:31], v[124:127], v[144:147], v[16:31]
	v_exp_f32_e32 v210, v52
	v_exp_f32_e32 v211, v53
	v_exp_f32_e32 v208, v54
	v_exp_f32_e32 v209, v55
	v_cvt_pk_bf16_f32 v124, v202, v203
	v_cvt_pk_bf16_f32 v125, v206, v207
	v_cvt_pk_bf16_f32 v126, v210, v211
	v_mfma_f32_32x32x16_bf16 v[0:15], v[140:143], v[144:147], v[0:15]
	v_cvt_pk_bf16_f32 v127, v208, v209
	v_exp_f32_e32 v204, v56
	v_exp_f32_e32 v205, v57
	v_exp_f32_e32 v212, v58
	v_exp_f32_e32 v213, v59
	v_exp_f32_e32 v216, v60
	v_exp_f32_e32 v217, v61
	v_mfma_f32_32x32x16_bf16 v[16:31], v[132:135], v[124:127], v[16:31]
	v_exp_f32_e32 v214, v62
	v_exp_f32_e32 v215, v63
	v_cvt_pk_bf16_f32 v60, v204, v205
	v_cvt_pk_bf16_f32 v61, v212, v213
	v_cvt_pk_bf16_f32 v62, v216, v217
	v_cvt_pk_bf16_f32 v63, v214, v215
	v_mfma_f32_32x32x16_bf16 v[0:15], v[128:131], v[124:127], v[0:15]
	v_mfma_f32_32x32x16_bf16 v[16:31], v[120:123], v[60:63], v[16:31]
	v_mfma_f32_32x32x16_bf16 v[0:15], v[116:119], v[60:63], v[0:15]
	s_waitcnt vmcnt(0)
	ds_write2_b64 v246, v[112:113], v[114:115] offset1:2
	s_waitcnt lgkmcnt(0)
	s_barrier
	ds_read_b128 v[48:51], v169
	ds_read_b128 v[52:55], v169 offset:32
	ds_read_b128 v[116:119], v169 offset:6656
	ds_read_b128 v[120:123], v169 offset:6688
	s_add_i32 m0, s70, 13312
	s_nop 0
	global_load_lds_dwordx4 v241, s[98:99]
	s_add_i32 m0, s73, s74
	global_load_dwordx4 v[112:115], v158, s[100:101] offset:384
	global_load_lds_dwordx4 v242, s[98:99]
	s_add_u32 s98, s98, 0x18000
	s_addc_u32 s99, s99, 0
	s_waitcnt lgkmcnt(3)
	v_mfma_f32_32x32x16_bf16 v[64:79], v[48:51], v[100:103], v[32:47]
	ds_read_b128 v[124:127], v169 offset:64
	ds_read_b128 v[128:131], v169 offset:96
	ds_read_b128 v[132:135], v169 offset:6720
	ds_read_b128 v[136:139], v169 offset:6752
	s_waitcnt lgkmcnt(4)
	v_mfma_f32_32x32x16_bf16 v[64:79], v[52:55], v[96:99], v[64:79]
	v_add_f32_e32 v220, v190, v206
	v_add_f32_e32 v221, v191, v207
	v_add_f32_e32 v222, v188, v202
	v_mfma_f32_32x32x16_bf16 v[48:63], v[116:119], v[100:103], v[32:47]
	v_add_f32_e32 v223, v189, v203
	v_add_f32_e32 v220, v152, v220
	v_add_f32_e32 v221, v153, v221
	v_mfma_f32_32x32x16_bf16 v[48:63], v[120:123], v[96:99], v[48:63]
	v_add_f32_e32 v224, v192, v208
	v_add_f32_e32 v225, v193, v209
	v_add_f32_e32 v222, v150, v222
	s_waitcnt lgkmcnt(1)
	v_mfma_f32_32x32x16_bf16 v[64:79], v[124:127], v[92:95], v[64:79]
	v_add_f32_e32 v223, v151, v223
	v_add_f32_e32 v226, v194, v210
	v_add_f32_e32 v227, v195, v211
	v_mfma_f32_32x32x16_bf16 v[48:63], v[132:135], v[92:95], v[48:63]
	v_add_f32_e32 v220, v224, v220
	v_add_f32_e32 v221, v225, v221
	v_add_f32_e32 v224, v196, v212
	v_mfma_f32_32x32x16_bf16 v[64:79], v[128:131], v[88:91], v[64:79]
	v_add_f32_e32 v225, v197, v213
	v_add_f32_e32 v226, v226, v222
	v_add_f32_e32 v227, v227, v223
	ds_read_b128 v[116:119], v169 offset:128
	ds_read_b128 v[120:123], v169 offset:160
	ds_read_b128 v[128:131], v169 offset:6784
	ds_read_b128 v[176:179], v169 offset:6816
	s_waitcnt lgkmcnt(3)
	v_mfma_f32_32x32x16_bf16 v[48:63], v[136:139], v[88:91], v[48:63]
	v_add_f32_e32 v222, v218, v204
	v_add_f32_e32 v223, v219, v205
	v_add_f32_e32 v220, v224, v220
	v_mfma_f32_32x32x16_bf16 v[64:79], v[116:119], v[84:87], v[64:79]
	v_add_f32_e32 v221, v225, v221
	v_add_f32_e32 v224, v198, v214
	v_add_f32_e32 v225, v199, v215
	ds_read_b128 v[136:139], v170 offset:35840
	ds_read_b128 v[124:127], v170 offset:35872
	s_waitcnt lgkmcnt(3)
	v_mfma_f32_32x32x16_bf16 v[48:63], v[128:131], v[84:87], v[48:63]
	v_add_f32_e32 v226, v222, v226
	v_add_f32_e32 v227, v223, v227
	v_add_f32_e32 v228, v200, v216
	v_mfma_f32_32x32x16_bf16 v[64:79], v[120:123], v[80:83], v[64:79]
	v_add_f32_e32 v229, v201, v217
	v_add_f32_e32 v152, v224, v220
	v_add_f32_e32 v153, v225, v221
	ds_read_b128 v[132:135], v170 offset:35904
	ds_read_b128 v[120:123], v170 offset:35936
	ds_read_b128 v[144:147], v170 offset:40448
	ds_read_b128 v[140:143], v170 offset:40480
	ds_read_b128 v[128:131], v170 offset:40512
	ds_read_b128 v[116:119], v170 offset:40544
	s_waitcnt lgkmcnt(8)
	v_mfma_f32_32x32x16_bf16 v[48:63], v[176:179], v[80:83], v[48:63]
	v_add_f32_e32 v150, v228, v226
	v_add_f32_e32 v151, v229, v227
	s_add_i32 s43, s43, 1
	s_nop 3
	v_exp_f32_e32 v188, v64
	v_exp_f32_e32 v189, v65
	v_exp_f32_e32 v190, v66
	v_exp_f32_e32 v191, v67
	v_exp_f32_e32 v194, v68
	v_exp_f32_e32 v195, v69
	v_exp_f32_e32 v192, v70
	v_exp_f32_e32 v193, v71
	v_cvt_pk_bf16_f32 v176, v188, v189
	v_cvt_pk_bf16_f32 v177, v190, v191
	v_cvt_pk_bf16_f32 v178, v194, v195
	v_cvt_pk_bf16_f32 v179, v192, v193
	v_exp_f32_e32 v196, v74
	v_exp_f32_e32 v197, v75
	s_waitcnt lgkmcnt(0)
; #define AT_QK_LD0(kb_) do { if constexpr (NEGM) { const LAS unsigned char* kbp_ = Kl + (kb_) * KBUF + r32 * KROWB + hi * 16; AT_KLD2(0); __builtin_amdgcn_sched_barrier(0); } } while (0)
; template <int DQK, int DV, int RH, bool NEGM> ...
;     ...
;         for (int t = 0; t < NT; ++t) {
;             const int kb = t & 1;
;             if (t + 1 < NT) AT_GLOAD(t + 1);
;             f32x16 p[RH][2];
;             AT_QK_LD0(kb); AT_QK(kb); AT_VLOAD(vs_cur); AT_SOFTMAX(); AT_PV(vs_cur);
;             if (t + 1 < NT) AT_LSTORE(kb ^ 1, vs_next);
;             __syncthreads();
;             vs_prev = vs_cur; vs_cur = vs_next; vs_next = (vs_next == 2) ? 0 : vs_next + 1;
	v_mfma_f32_32x32x16_bf16 v[16:31], v[136:139], v[176:179], v[16:31]
	v_exp_f32_e32 v218, v72
	v_exp_f32_e32 v219, v73
	v_exp_f32_e32 v200, v76
	v_exp_f32_e32 v201, v77
	v_exp_f32_e32 v198, v78
	v_exp_f32_e32 v199, v79
	v_exp_f32_e32 v202, v48
	v_mfma_f32_32x32x16_bf16 v[0:15], v[144:147], v[176:179], v[0:15]
	v_cvt_pk_bf16_f32 v144, v218, v219
	v_cvt_pk_bf16_f32 v145, v196, v197
	v_cvt_pk_bf16_f32 v146, v200, v201
	v_cvt_pk_bf16_f32 v147, v198, v199
	v_exp_f32_e32 v203, v49
	v_exp_f32_e32 v206, v50
	v_exp_f32_e32 v207, v51
	v_mfma_f32_32x32x16_bf16 v[16:31], v[124:127], v[144:147], v[16:31]
	v_exp_f32_e32 v210, v52
	v_exp_f32_e32 v211, v53
	v_exp_f32_e32 v208, v54
	v_exp_f32_e32 v209, v55
	v_cvt_pk_bf16_f32 v124, v202, v203
	v_cvt_pk_bf16_f32 v125, v206, v207
	v_cvt_pk_bf16_f32 v126, v210, v211
	v_mfma_f32_32x32x16_bf16 v[0:15], v[140:143], v[144:147], v[0:15]
	v_cvt_pk_bf16_f32 v127, v208, v209
	v_exp_f32_e32 v204, v56
	v_exp_f32_e32 v205, v57
	v_exp_f32_e32 v212, v58
	v_exp_f32_e32 v213, v59
	v_exp_f32_e32 v216, v60
	v_exp_f32_e32 v217, v61
	v_mfma_f32_32x32x16_bf16 v[16:31], v[132:135], v[124:127], v[16:31]
	v_exp_f32_e32 v214, v62
	v_exp_f32_e32 v215, v63
	v_cvt_pk_bf16_f32 v60, v204, v205
	v_cvt_pk_bf16_f32 v61, v212, v213
	v_cvt_pk_bf16_f32 v62, v216, v217
	v_cvt_pk_bf16_f32 v63, v214, v215
	v_mfma_f32_32x32x16_bf16 v[0:15], v[128:131], v[124:127], v[0:15]
	v_mfma_f32_32x32x16_bf16 v[16:31], v[120:123], v[60:63], v[16:31]
	v_mfma_f32_32x32x16_bf16 v[0:15], v[116:119], v[60:63], v[0:15]
	s_waitcnt vmcnt(0)
	ds_write2_b64 v247, v[112:113], v[114:115] offset1:2
	s_waitcnt lgkmcnt(0)
	s_barrier
	ds_read_b128 v[48:51], v169 offset:13312
	ds_read_b128 v[52:55], v169 offset:13344
	ds_read_b128 v[116:119], v169 offset:19968
	ds_read_b128 v[120:123], v169 offset:20000
	s_mov_b32 m0, s70
	s_nop 0
	global_load_lds_dwordx4 v241, s[98:99]
	s_mov_b32 m0, s73
	global_load_dwordx4 v[112:115], v158, s[100:101] offset:512
	global_load_lds_dwordx4 v242, s[98:99]
	s_add_u32 s98, s98, 0x18000
	s_addc_u32 s99, s99, 0
	s_waitcnt lgkmcnt(3)
	v_mfma_f32_32x32x16_bf16 v[64:79], v[48:51], v[100:103], v[32:47]
	ds_read_b128 v[124:127], v169 offset:13376
	ds_read_b128 v[128:131], v169 offset:13408
	ds_read_b128 v[132:135], v169 offset:20032
	ds_read_b128 v[136:139], v169 offset:20064
	s_waitcnt lgkmcnt(4)
	v_mfma_f32_32x32x16_bf16 v[64:79], v[52:55], v[96:99], v[64:79]
	v_add_f32_e32 v220, v190, v206
	v_add_f32_e32 v221, v191, v207
	v_add_f32_e32 v222, v188, v202
	v_mfma_f32_32x32x16_bf16 v[48:63], v[116:119], v[100:103], v[32:47]
	v_add_f32_e32 v223, v189, v203
	v_add_f32_e32 v220, v152, v220
	v_add_f32_e32 v221, v153, v221
	v_mfma_f32_32x32x16_bf16 v[48:63], v[120:123], v[96:99], v[48:63]
	v_add_f32_e32 v224, v192, v208
	v_add_f32_e32 v225, v193, v209
	v_add_f32_e32 v222, v150, v222
	s_waitcnt lgkmcnt(1)
	v_mfma_f32_32x32x16_bf16 v[64:79], v[124:127], v[92:95], v[64:79]
	v_add_f32_e32 v223, v151, v223
	v_add_f32_e32 v226, v194, v210
	v_add_f32_e32 v227, v195, v211
	v_mfma_f32_32x32x16_bf16 v[48:63], v[132:135], v[92:95], v[48:63]
	v_add_f32_e32 v220, v224, v220
	v_add_f32_e32 v221, v225, v221
	v_add_f32_e32 v224, v196, v212
	v_mfma_f32_32x32x16_bf16 v[64:79], v[128:131], v[88:91], v[64:79]
	v_add_f32_e32 v225, v197, v213
	v_add_f32_e32 v226, v226, v222
	v_add_f32_e32 v227, v227, v223
	ds_read_b128 v[116:119], v169 offset:13440
	ds_read_b128 v[120:123], v169 offset:13472
	ds_read_b128 v[128:131], v169 offset:20096
	ds_read_b128 v[176:179], v169 offset:20128
	s_waitcnt lgkmcnt(3)
	v_mfma_f32_32x32x16_bf16 v[48:63], v[136:139], v[88:91], v[48:63]
	v_add_f32_e32 v222, v218, v204
	v_add_f32_e32 v223, v219, v205
	v_add_f32_e32 v220, v224, v220
	v_mfma_f32_32x32x16_bf16 v[64:79], v[116:119], v[84:87], v[64:79]
	v_add_f32_e32 v221, v225, v221
	v_add_f32_e32 v224, v198, v214
	v_add_f32_e32 v225, v199, v215
	ds_read_b128 v[136:139], v170 offset:45056
	ds_read_b128 v[124:127], v170 offset:45088
	s_waitcnt lgkmcnt(3)
	v_mfma_f32_32x32x16_bf16 v[48:63], v[128:131], v[84:87], v[48:63]
	v_add_f32_e32 v226, v222, v226
	v_add_f32_e32 v227, v223, v227
	v_add_f32_e32 v228, v200, v216
	v_mfma_f32_32x32x16_bf16 v[64:79], v[120:123], v[80:83], v[64:79]
	v_add_f32_e32 v229, v201, v217
	v_add_f32_e32 v152, v224, v220
	v_add_f32_e32 v153, v225, v221
	ds_read_b128 v[132:135], v170 offset:45120
	ds_read_b128 v[120:123], v170 offset:45152
	ds_read_b128 v[144:147], v170 offset:49664
	ds_read_b128 v[140:143], v170 offset:49696
	ds_read_b128 v[128:131], v170 offset:49728
	ds_read_b128 v[116:119], v170 offset:49760
	s_waitcnt lgkmcnt(8)
	v_mfma_f32_32x32x16_bf16 v[48:63], v[176:179], v[80:83], v[48:63]
	v_add_f32_e32 v150, v228, v226
	v_add_f32_e32 v151, v229, v227
	s_add_i32 s43, s43, 1
	s_nop 3
	v_exp_f32_e32 v188, v64
	v_exp_f32_e32 v189, v65
	v_exp_f32_e32 v190, v66
	v_exp_f32_e32 v191, v67
	v_exp_f32_e32 v194, v68
	v_exp_f32_e32 v195, v69
	v_exp_f32_e32 v192, v70
	v_exp_f32_e32 v193, v71
	v_cvt_pk_bf16_f32 v176, v188, v189
	v_cvt_pk_bf16_f32 v177, v190, v191
	v_cvt_pk_bf16_f32 v178, v194, v195
	v_cvt_pk_bf16_f32 v179, v192, v193
	v_exp_f32_e32 v196, v74
	v_exp_f32_e32 v197, v75
	s_waitcnt lgkmcnt(0)
	v_mfma_f32_32x32x16_bf16 v[16:31], v[136:139], v[176:179], v[16:31]
	v_exp_f32_e32 v218, v72
	v_exp_f32_e32 v219, v73
	v_exp_f32_e32 v200, v76
	v_exp_f32_e32 v201, v77
	v_exp_f32_e32 v198, v78
	v_exp_f32_e32 v199, v79
	v_exp_f32_e32 v202, v48
	v_mfma_f32_32x32x16_bf16 v[0:15], v[144:147], v[176:179], v[0:15]
	v_cvt_pk_bf16_f32 v144, v218, v219
	v_cvt_pk_bf16_f32 v145, v196, v197
	v_cvt_pk_bf16_f32 v146, v200, v201
	v_cvt_pk_bf16_f32 v147, v198, v199
	v_exp_f32_e32 v203, v49
	v_exp_f32_e32 v206, v50
	v_exp_f32_e32 v207, v51
	v_mfma_f32_32x32x16_bf16 v[16:31], v[124:127], v[144:147], v[16:31]
	v_exp_f32_e32 v210, v52
	v_exp_f32_e32 v211, v53
	v_exp_f32_e32 v208, v54
	v_exp_f32_e32 v209, v55
	v_cvt_pk_bf16_f32 v124, v202, v203
	v_cvt_pk_bf16_f32 v125, v206, v207
	v_cvt_pk_bf16_f32 v126, v210, v211
	v_mfma_f32_32x32x16_bf16 v[0:15], v[140:143], v[144:147], v[0:15]
	v_cvt_pk_bf16_f32 v127, v208, v209
	v_exp_f32_e32 v204, v56
	v_exp_f32_e32 v205, v57
	v_exp_f32_e32 v212, v58
	v_exp_f32_e32 v213, v59
	v_exp_f32_e32 v216, v60
	v_exp_f32_e32 v217, v61
	v_mfma_f32_32x32x16_bf16 v[16:31], v[132:135], v[124:127], v[16:31]
	v_exp_f32_e32 v214, v62
	v_exp_f32_e32 v215, v63
	v_cvt_pk_bf16_f32 v60, v204, v205
	v_cvt_pk_bf16_f32 v61, v212, v213
	v_cvt_pk_bf16_f32 v62, v216, v217
	v_cvt_pk_bf16_f32 v63, v214, v215
	v_mfma_f32_32x32x16_bf16 v[0:15], v[128:131], v[124:127], v[0:15]
	v_mfma_f32_32x32x16_bf16 v[16:31], v[120:123], v[60:63], v[16:31]
	v_mfma_f32_32x32x16_bf16 v[0:15], v[116:119], v[60:63], v[0:15]
	s_waitcnt vmcnt(0)
	ds_write2_b64 v243, v[112:113], v[114:115] offset1:2
	s_waitcnt lgkmcnt(0)
	s_barrier
	ds_read_b128 v[48:51], v169
	ds_read_b128 v[52:55], v169 offset:32
	ds_read_b128 v[116:119], v169 offset:6656
	ds_read_b128 v[120:123], v169 offset:6688
	s_add_i32 m0, s70, 13312
	s_nop 0
	global_load_lds_dwordx4 v241, s[98:99]
	s_add_i32 m0, s73, s74
	global_load_dwordx4 v[112:115], v158, s[100:101] offset:640
	global_load_lds_dwordx4 v242, s[98:99]
	s_add_u32 s98, s98, 0x18000
	s_addc_u32 s99, s99, 0
	s_waitcnt lgkmcnt(3)
	v_mfma_f32_32x32x16_bf16 v[64:79], v[48:51], v[100:103], v[32:47]
	ds_read_b128 v[124:127], v169 offset:64
	ds_read_b128 v[128:131], v169 offset:96
	ds_read_b128 v[132:135], v169 offset:6720
	ds_read_b128 v[136:139], v169 offset:6752
	s_waitcnt lgkmcnt(4)
	v_mfma_f32_32x32x16_bf16 v[64:79], v[52:55], v[96:99], v[64:79]
	v_add_f32_e32 v220, v190, v206
	v_add_f32_e32 v221, v191, v207
	v_add_f32_e32 v222, v188, v202
	v_mfma_f32_32x32x16_bf16 v[48:63], v[116:119], v[100:103], v[32:47]
	v_add_f32_e32 v223, v189, v203
	v_add_f32_e32 v220, v152, v220
	v_add_f32_e32 v221, v153, v221
	v_mfma_f32_32x32x16_bf16 v[48:63], v[120:123], v[96:99], v[48:63]
	v_add_f32_e32 v224, v192, v208
	v_add_f32_e32 v225, v193, v209
	v_add_f32_e32 v222, v150, v222
	s_waitcnt lgkmcnt(1)
	v_mfma_f32_32x32x16_bf16 v[64:79], v[124:127], v[92:95], v[64:79]
	v_add_f32_e32 v223, v151, v223
	v_add_f32_e32 v226, v194, v210
	v_add_f32_e32 v227, v195, v211
	v_mfma_f32_32x32x16_bf16 v[48:63], v[132:135], v[92:95], v[48:63]
	v_add_f32_e32 v220, v224, v220
	v_add_f32_e32 v221, v225, v221
	v_add_f32_e32 v224, v196, v212
	v_mfma_f32_32x32x16_bf16 v[64:79], v[128:131], v[88:91], v[64:79]
	v_add_f32_e32 v225, v197, v213
	v_add_f32_e32 v226, v226, v222
	v_add_f32_e32 v227, v227, v223
	ds_read_b128 v[116:119], v169 offset:128
	ds_read_b128 v[120:123], v169 offset:160
	ds_read_b128 v[128:131], v169 offset:6784
	ds_read_b128 v[176:179], v169 offset:6816
	s_waitcnt lgkmcnt(3)
	v_mfma_f32_32x32x16_bf16 v[48:63], v[136:139], v[88:91], v[48:63]
	v_add_f32_e32 v222, v218, v204
	v_add_f32_e32 v223, v219, v205
	v_add_f32_e32 v220, v224, v220
	v_mfma_f32_32x32x16_bf16 v[64:79], v[116:119], v[84:87], v[64:79]
	v_add_f32_e32 v221, v225, v221
	v_add_f32_e32 v224, v198, v214
	v_add_f32_e32 v225, v199, v215
	ds_read_b128 v[136:139], v170 offset:26624
	ds_read_b128 v[124:127], v170 offset:26656
	s_waitcnt lgkmcnt(3)
	v_mfma_f32_32x32x16_bf16 v[48:63], v[128:131], v[84:87], v[48:63]
	v_add_f32_e32 v226, v222, v226
	v_add_f32_e32 v227, v223, v227
	v_add_f32_e32 v228, v200, v216
	v_mfma_f32_32x32x16_bf16 v[64:79], v[120:123], v[80:83], v[64:79]
	v_add_f32_e32 v229, v201, v217
	v_add_f32_e32 v152, v224, v220
	v_add_f32_e32 v153, v225, v221
	ds_read_b128 v[132:135], v170 offset:26688
	ds_read_b128 v[120:123], v170 offset:26720
	ds_read_b128 v[144:147], v170 offset:31232
	ds_read_b128 v[140:143], v170 offset:31264
	ds_read_b128 v[128:131], v170 offset:31296
	ds_read_b128 v[116:119], v170 offset:31328
	s_waitcnt lgkmcnt(8)
	v_mfma_f32_32x32x16_bf16 v[48:63], v[176:179], v[80:83], v[48:63]
	v_add_f32_e32 v150, v228, v226
	v_add_f32_e32 v151, v229, v227
	s_add_i32 s43, s43, 1
	s_nop 3
	v_exp_f32_e32 v188, v64
	v_exp_f32_e32 v189, v65
	v_exp_f32_e32 v190, v66
	v_exp_f32_e32 v191, v67
	v_exp_f32_e32 v194, v68
	v_exp_f32_e32 v195, v69
	v_exp_f32_e32 v192, v70
	v_exp_f32_e32 v193, v71
	v_cvt_pk_bf16_f32 v176, v188, v189
	v_cvt_pk_bf16_f32 v177, v190, v191
	v_cvt_pk_bf16_f32 v178, v194, v195
	v_cvt_pk_bf16_f32 v179, v192, v193
	v_exp_f32_e32 v196, v74
	v_exp_f32_e32 v197, v75
	s_waitcnt lgkmcnt(0)
	v_mfma_f32_32x32x16_bf16 v[16:31], v[136:139], v[176:179], v[16:31]
	v_exp_f32_e32 v218, v72
	v_exp_f32_e32 v219, v73
	v_exp_f32_e32 v200, v76
	v_exp_f32_e32 v201, v77
	v_exp_f32_e32 v198, v78
	v_exp_f32_e32 v199, v79
	v_exp_f32_e32 v202, v48
	v_mfma_f32_32x32x16_bf16 v[0:15], v[144:147], v[176:179], v[0:15]
	v_cvt_pk_bf16_f32 v144, v218, v219
	v_cvt_pk_bf16_f32 v145, v196, v197
	v_cvt_pk_bf16_f32 v146, v200, v201
	v_cvt_pk_bf16_f32 v147, v198, v199
	v_exp_f32_e32 v203, v49
	v_exp_f32_e32 v206, v50
	v_exp_f32_e32 v207, v51
	v_mfma_f32_32x32x16_bf16 v[16:31], v[124:127], v[144:147], v[16:31]
	v_exp_f32_e32 v210, v52
	v_exp_f32_e32 v211, v53
	v_exp_f32_e32 v208, v54
	v_exp_f32_e32 v209, v55
	v_cvt_pk_bf16_f32 v124, v202, v203
	v_cvt_pk_bf16_f32 v125, v206, v207
	v_cvt_pk_bf16_f32 v126, v210, v211
	v_mfma_f32_32x32x16_bf16 v[0:15], v[140:143], v[144:147], v[0:15]
	v_cvt_pk_bf16_f32 v127, v208, v209
	v_exp_f32_e32 v204, v56
	v_exp_f32_e32 v205, v57
	v_exp_f32_e32 v212, v58
	v_exp_f32_e32 v213, v59
	v_exp_f32_e32 v216, v60
	v_exp_f32_e32 v217, v61
	v_mfma_f32_32x32x16_bf16 v[16:31], v[132:135], v[124:127], v[16:31]
	v_exp_f32_e32 v214, v62
	v_exp_f32_e32 v215, v63
	v_cvt_pk_bf16_f32 v60, v204, v205
	v_cvt_pk_bf16_f32 v61, v212, v213
	v_cvt_pk_bf16_f32 v62, v216, v217
	v_cvt_pk_bf16_f32 v63, v214, v215
	v_mfma_f32_32x32x16_bf16 v[0:15], v[128:131], v[124:127], v[0:15]
	v_mfma_f32_32x32x16_bf16 v[16:31], v[120:123], v[60:63], v[16:31]
	v_mfma_f32_32x32x16_bf16 v[0:15], v[116:119], v[60:63], v[0:15]
	s_waitcnt vmcnt(0)
	ds_write2_b64 v246, v[112:113], v[114:115] offset1:2
	v_max3_f32 v148, v150, v151, v152
	v_max_f32_e32 v148, v148, v153
	v_cmp_nge_f32_e32 vcc, 0x49800000, v148
	s_cbranch_vccnz .Lmla_renorm

.Lmla_renorm_ok:
	v_frexp_exp_i32_f32_e32 v160, v148
	v_max_i32_e32 v160, 0, v160
	v_cvt_f32_i32_e32 v161, v160
	v_sub_u32_e32 v160, 0, v160
	v_ldexp_f32 v160, 1.0, v160
	v_add_f32_e32 v168, v168, v161
	v_xor_b32_e32 v32, 0x80000000, v168
	v_mov_b32_e32 v33, v32
	v_mov_b32_e32 v34, v32
	v_mov_b32_e32 v35, v32
	v_mov_b32_e32 v36, v32
	v_mov_b32_e32 v37, v32
	v_mov_b32_e32 v38, v32
	v_mov_b32_e32 v39, v32
	v_mov_b32_e32 v40, v32
	v_mov_b32_e32 v41, v32
	v_mov_b32_e32 v42, v32
	v_mov_b32_e32 v43, v32
	v_mov_b32_e32 v44, v32
	v_mov_b32_e32 v45, v32
	v_mov_b32_e32 v46, v32
	v_mov_b32_e32 v47, v32
	v_pk_mul_f32 v[0:1], v[0:1], v[160:161] op_sel_hi:[1,0]
	v_pk_mul_f32 v[2:3], v[2:3], v[160:161] op_sel_hi:[1,0]
	v_pk_mul_f32 v[4:5], v[4:5], v[160:161] op_sel_hi:[1,0]
	v_pk_mul_f32 v[6:7], v[6:7], v[160:161] op_sel_hi:[1,0]
	v_pk_mul_f32 v[8:9], v[8:9], v[160:161] op_sel_hi:[1,0]
	v_pk_mul_f32 v[10:11], v[10:11], v[160:161] op_sel_hi:[1,0]
	v_pk_mul_f32 v[12:13], v[12:13], v[160:161] op_sel_hi:[1,0]
	v_pk_mul_f32 v[14:15], v[14:15], v[160:161] op_sel_hi:[1,0]
	v_pk_mul_f32 v[16:17], v[16:17], v[160:161] op_sel_hi:[1,0]
	v_pk_mul_f32 v[18:19], v[18:19], v[160:161] op_sel_hi:[1,0]
	v_pk_mul_f32 v[20:21], v[20:21], v[160:161] op_sel_hi:[1,0]
	v_pk_mul_f32 v[22:23], v[22:23], v[160:161] op_sel_hi:[1,0]
	v_pk_mul_f32 v[24:25], v[24:25], v[160:161] op_sel_hi:[1,0]
	v_pk_mul_f32 v[26:27], v[26:27], v[160:161] op_sel_hi:[1,0]
	v_pk_mul_f32 v[28:29], v[28:29], v[160:161] op_sel_hi:[1,0]
	v_pk_mul_f32 v[30:31], v[30:31], v[160:161] op_sel_hi:[1,0]
	v_pk_mul_f32 v[150:151], v[150:151], v[160:161] op_sel_hi:[1,0]
	v_pk_mul_f32 v[152:153], v[152:153], v[160:161] op_sel_hi:[1,0]
	v_pk_mul_f32 v[188:189], v[188:189], v[160:161] op_sel_hi:[1,0]
	v_pk_mul_f32 v[190:191], v[190:191], v[160:161] op_sel_hi:[1,0]
	v_pk_mul_f32 v[192:193], v[192:193], v[160:161] op_sel_hi:[1,0]
	v_pk_mul_f32 v[194:195], v[194:195], v[160:161] op_sel_hi:[1,0]
	v_pk_mul_f32 v[196:197], v[196:197], v[160:161] op_sel_hi:[1,0]
	v_pk_mul_f32 v[198:199], v[198:199], v[160:161] op_sel_hi:[1,0]
	v_pk_mul_f32 v[200:201], v[200:201], v[160:161] op_sel_hi:[1,0]
	v_pk_mul_f32 v[202:203], v[202:203], v[160:161] op_sel_hi:[1,0]
	v_pk_mul_f32 v[204:205], v[204:205], v[160:161] op_sel_hi:[1,0]
	v_pk_mul_f32 v[206:207], v[206:207], v[160:161] op_sel_hi:[1,0]
	v_pk_mul_f32 v[208:209], v[208:209], v[160:161] op_sel_hi:[1,0]
	v_pk_mul_f32 v[210:211], v[210:211], v[160:161] op_sel_hi:[1,0]
	v_pk_mul_f32 v[212:213], v[212:213], v[160:161] op_sel_hi:[1,0]
	v_pk_mul_f32 v[214:215], v[214:215], v[160:161] op_sel_hi:[1,0]
	v_pk_mul_f32 v[216:217], v[216:217], v[160:161] op_sel_hi:[1,0]
	v_pk_mul_f32 v[218:219], v[218:219], v[160:161] op_sel_hi:[1,0]
	s_branch .Lmla_renorm_back

; template <int DQK, int DV, int RH, bool NEGM> ...
;     ...
; #pragma unroll
;     for (int hh = 0; hh < RH; ++hh) {
;         float l = (lacc[hh][0] + lacc[hh][1]) + (lacc[hh][2] + lacc[hh][3]); l += __shfl_xor(l, 32);
;         const float inv = 1.f / l;
.Lmla_exit:
	v_pk_add_f32 v[220:221], v[190:191], v[206:207]
	v_pk_add_f32 v[222:223], v[188:189], v[202:203]
	v_pk_add_f32 v[220:221], v[152:153], v[220:221]
	v_pk_add_f32 v[224:225], v[192:193], v[208:209]
	v_pk_add_f32 v[222:223], v[150:151], v[222:223]
	v_pk_add_f32 v[226:227], v[194:195], v[210:211]
	v_pk_add_f32 v[220:221], v[224:225], v[220:221]
	v_pk_add_f32 v[224:225], v[196:197], v[212:213]
	v_pk_add_f32 v[226:227], v[226:227], v[222:223]
	v_pk_add_f32 v[222:223], v[218:219], v[204:205]
	v_pk_add_f32 v[220:221], v[224:225], v[220:221]
	v_pk_add_f32 v[224:225], v[198:199], v[214:215]
	v_pk_add_f32 v[226:227], v[222:223], v[226:227]
	v_pk_add_f32 v[228:229], v[200:201], v[216:217]
	v_pk_add_f32 v[152:153], v[224:225], v[220:221]
	v_pk_add_f32 v[150:151], v[228:229], v[226:227]
	s_mov_b32 s21, 0
	v_max3_f32 v148, v150, v151, v152
	v_max_f32_e32 v148, v148, v153
	v_cmp_nge_f32_e32 vcc, 0x53800000, v148
	s_cbranch_vccz .Lmla_exit_ok
	s_mov_b32 s64, 1
